# phase 0 filter-MLP rewritten (weights in registers, v_readlane broadcast, no LDS/barriers); phase 6 part 2 rewritten (double-buffered LDS transpose, prefetch one item ahead, hoisted conv constants)
# speedup vs baseline: 1.0147x; 1.0147x over previous
; DI void phase_prep(const P& p, int bid, int nb) {
;     ...
;     for (int it = bid; it < 2048; it += nb) {
;       const int t = it * 8 + tl;
;       if (j < 33) { float v; if (j == 0) v = (float)t * (1.f / 16383.f); else { int i = (j - 1) & 15; float fr = 1e-4f + (float)i * ((15.f - 1e-4f) / 15.f); float turns = fr * ((float)t * (1.f / 16384.f)); turns -= floorf(turns);
;           v = (j <= 16) ? __builtin_amdgcn_cosf(turns) : -__builtin_amdgcn_sinf(turns); } zb[tl * 36 + j] = v; }
;       __syncthreads();
;       float acc = p.emb_b[j];
; #pragma unroll 3
;       for (int i = 0; i < 33; ++i) acc += zb[tl * 36 + i] * p.emb_w[i * 64 + j];
;       ha[tl * 64 + j] = __sinf(p.freq[j] * acc);
;       __syncthreads();
;       acc = p.mlp_b[j];
; #pragma unroll 8
;       for (int i = 0; i < 64; ++i) acc += ha[tl * 64 + i] * p.mlp_w[i * 64 + j];
.LBB0_27:
	s_cmpk_gt_i32 s2, 0x7ff
	s_cbranch_scc1 .LBB0_42
	s_load_dwordx16 s[16:31], s[0:1], 0x80
	v_and_b32_e32 v1, 0x3ff, v0
	v_and_b32_e32 v215, 63, v1
	v_lshrrev_b32_e32 v2, 6, v1
	v_lshlrev_b32_e32 v216, 2, v215
	v_readfirstlane_b32 s9, v2
	v_lshlrev_b32_e32 v217, 1, v215
	v_add_u32_e32 v3, -1, v215
	v_and_b32_e32 v3, 15, v3
	v_cvt_f32_ubyte0_e32 v3, v3
	v_mov_b32_e32 v214, 0x38d1b717
	v_fmac_f32_e32 v214, 0x3f7fff90, v3
	v_cmp_ne_u32_e64 s[4:5], 0, v215
	v_cmp_gt_u32_e64 s[6:7], 17, v215
	s_waitcnt lgkmcnt(0)
	s_add_u32 s14, s20, 0x0
	s_addc_u32 s15, s21, 0
	global_load_dword v40, v216, s[14:15]
	global_load_dword v41, v216, s[14:15] offset:256
	global_load_dword v42, v216, s[14:15] offset:512
	global_load_dword v43, v216, s[14:15] offset:768
	global_load_dword v44, v216, s[14:15] offset:1024
	global_load_dword v45, v216, s[14:15] offset:1280
	global_load_dword v46, v216, s[14:15] offset:1536
	global_load_dword v47, v216, s[14:15] offset:1792
	global_load_dword v48, v216, s[14:15] offset:2048
	global_load_dword v49, v216, s[14:15] offset:2304
	global_load_dword v50, v216, s[14:15] offset:2560
	global_load_dword v51, v216, s[14:15] offset:2816
	global_load_dword v52, v216, s[14:15] offset:3072
	global_load_dword v53, v216, s[14:15] offset:3328
	global_load_dword v54, v216, s[14:15] offset:3584
	global_load_dword v55, v216, s[14:15] offset:3840
	s_add_u32 s14, s20, 0x1000
	s_addc_u32 s15, s21, 0
	global_load_dword v56, v216, s[14:15]
	global_load_dword v57, v216, s[14:15] offset:256
	global_load_dword v58, v216, s[14:15] offset:512
	global_load_dword v59, v216, s[14:15] offset:768
	global_load_dword v60, v216, s[14:15] offset:1024
	global_load_dword v61, v216, s[14:15] offset:1280
	global_load_dword v62, v216, s[14:15] offset:1536
	global_load_dword v63, v216, s[14:15] offset:1792
	global_load_dword v64, v216, s[14:15] offset:2048
	global_load_dword v65, v216, s[14:15] offset:2304
	global_load_dword v66, v216, s[14:15] offset:2560
	global_load_dword v67, v216, s[14:15] offset:2816
	global_load_dword v68, v216, s[14:15] offset:3072
	global_load_dword v69, v216, s[14:15] offset:3328
	global_load_dword v70, v216, s[14:15] offset:3584
	global_load_dword v71, v216, s[14:15] offset:3840
	s_add_u32 s14, s20, 0x2000
	s_addc_u32 s15, s21, 0
	global_load_dword v72, v216, s[14:15]
	s_add_u32 s14, s24, 0x0
	s_addc_u32 s15, s25, 0
	global_load_dword v80, v216, s[14:15]
	global_load_dword v81, v216, s[14:15] offset:256
	global_load_dword v82, v216, s[14:15] offset:512
	global_load_dword v83, v216, s[14:15] offset:768
	global_load_dword v84, v216, s[14:15] offset:1024
	global_load_dword v85, v216, s[14:15] offset:1280
	global_load_dword v86, v216, s[14:15] offset:1536
	global_load_dword v87, v216, s[14:15] offset:1792
	global_load_dword v88, v216, s[14:15] offset:2048
	global_load_dword v89, v216, s[14:15] offset:2304
	global_load_dword v90, v216, s[14:15] offset:2560
	global_load_dword v91, v216, s[14:15] offset:2816
	global_load_dword v92, v216, s[14:15] offset:3072
	global_load_dword v93, v216, s[14:15] offset:3328
	global_load_dword v94, v216, s[14:15] offset:3584
	global_load_dword v95, v216, s[14:15] offset:3840
	s_add_u32 s14, s24, 0x1000
	s_addc_u32 s15, s25, 0
	global_load_dword v96, v216, s[14:15]
	global_load_dword v97, v216, s[14:15] offset:256
	global_load_dword v98, v216, s[14:15] offset:512
	global_load_dword v99, v216, s[14:15] offset:768
	global_load_dword v100, v216, s[14:15] offset:1024
	global_load_dword v101, v216, s[14:15] offset:1280
	global_load_dword v102, v216, s[14:15] offset:1536
	global_load_dword v103, v216, s[14:15] offset:1792
	global_load_dword v104, v216, s[14:15] offset:2048
	global_load_dword v105, v216, s[14:15] offset:2304
	global_load_dword v106, v216, s[14:15] offset:2560
	global_load_dword v107, v216, s[14:15] offset:2816
	global_load_dword v108, v216, s[14:15] offset:3072
	global_load_dword v109, v216, s[14:15] offset:3328
	global_load_dword v110, v216, s[14:15] offset:3584
	global_load_dword v111, v216, s[14:15] offset:3840
	s_add_u32 s14, s24, 0x2000
	s_addc_u32 s15, s25, 0
	global_load_dword v112, v216, s[14:15]
	global_load_dword v113, v216, s[14:15] offset:256
	global_load_dword v114, v216, s[14:15] offset:512
	global_load_dword v115, v216, s[14:15] offset:768
	global_load_dword v116, v216, s[14:15] offset:1024
	global_load_dword v117, v216, s[14:15] offset:1280
	global_load_dword v118, v216, s[14:15] offset:1536
	global_load_dword v119, v216, s[14:15] offset:1792
	global_load_dword v120, v216, s[14:15] offset:2048
	global_load_dword v121, v216, s[14:15] offset:2304
	global_load_dword v122, v216, s[14:15] offset:2560
	global_load_dword v123, v216, s[14:15] offset:2816
	global_load_dword v124, v216, s[14:15] offset:3072
	global_load_dword v125, v216, s[14:15] offset:3328
	global_load_dword v126, v216, s[14:15] offset:3584
	global_load_dword v127, v216, s[14:15] offset:3840
	s_add_u32 s14, s24, 0x3000
	s_addc_u32 s15, s25, 0
	global_load_dword v128, v216, s[14:15]
	global_load_dword v129, v216, s[14:15] offset:256
	global_load_dword v130, v216, s[14:15] offset:512
	global_load_dword v131, v216, s[14:15] offset:768
	global_load_dword v132, v216, s[14:15] offset:1024
	global_load_dword v133, v216, s[14:15] offset:1280
	global_load_dword v134, v216, s[14:15] offset:1536
	global_load_dword v135, v216, s[14:15] offset:1792
	global_load_dword v136, v216, s[14:15] offset:2048
	global_load_dword v137, v216, s[14:15] offset:2304
	global_load_dword v138, v216, s[14:15] offset:2560
	global_load_dword v139, v216, s[14:15] offset:2816
	global_load_dword v140, v216, s[14:15] offset:3072
; DI void phase_prep(const P& p, int bid, int nb) {
;     ...
;     for (int it = bid; it < 2048; it += nb) {
;       const int t = it * 8 + tl;
;       if (j < 33) { float v; if (j == 0) v = (float)t * (1.f / 16383.f); else { int i = (j - 1) & 15; float fr = 1e-4f + (float)i * ((15.f - 1e-4f) / 15.f); float turns = fr * ((float)t * (1.f / 16384.f)); turns -= floorf(turns);
;           v = (j <= 16) ? __builtin_amdgcn_cosf(turns) : -__builtin_amdgcn_sinf(turns); } zb[tl * 36 + j] = v; }
;       __syncthreads();
;       float acc = p.emb_b[j];
; #pragma unroll 3
;       for (int i = 0; i < 33; ++i) acc += zb[tl * 36 + i] * p.emb_w[i * 64 + j];
	global_load_dword v141, v216, s[14:15] offset:3328
	global_load_dword v142, v216, s[14:15] offset:3584
	global_load_dword v143, v216, s[14:15] offset:3840
	s_add_u32 s24, s24, 0x4000
	s_addc_u32 s25, s25, 0
	s_add_u32 s14, s24, 0x0
	s_addc_u32 s15, s25, 0
	global_load_dword v144, v216, s[14:15]
	global_load_dword v145, v216, s[14:15] offset:256
	global_load_dword v146, v216, s[14:15] offset:512
	global_load_dword v147, v216, s[14:15] offset:768
	global_load_dword v148, v216, s[14:15] offset:1024
	global_load_dword v149, v216, s[14:15] offset:1280
	global_load_dword v150, v216, s[14:15] offset:1536
	global_load_dword v151, v216, s[14:15] offset:1792
	global_load_dword v152, v216, s[14:15] offset:2048
	global_load_dword v153, v216, s[14:15] offset:2304
	global_load_dword v154, v216, s[14:15] offset:2560
	global_load_dword v155, v216, s[14:15] offset:2816
	global_load_dword v156, v216, s[14:15] offset:3072
	global_load_dword v157, v216, s[14:15] offset:3328
	global_load_dword v158, v216, s[14:15] offset:3584
	global_load_dword v159, v216, s[14:15] offset:3840
	s_add_u32 s14, s24, 0x1000
	s_addc_u32 s15, s25, 0
	global_load_dword v160, v216, s[14:15]
	global_load_dword v161, v216, s[14:15] offset:256
	global_load_dword v162, v216, s[14:15] offset:512
	global_load_dword v163, v216, s[14:15] offset:768
	global_load_dword v164, v216, s[14:15] offset:1024
	global_load_dword v165, v216, s[14:15] offset:1280
	global_load_dword v166, v216, s[14:15] offset:1536
	global_load_dword v167, v216, s[14:15] offset:1792
	global_load_dword v168, v216, s[14:15] offset:2048
	global_load_dword v169, v216, s[14:15] offset:2304
	global_load_dword v170, v216, s[14:15] offset:2560
	global_load_dword v171, v216, s[14:15] offset:2816
	global_load_dword v172, v216, s[14:15] offset:3072
	global_load_dword v173, v216, s[14:15] offset:3328
	global_load_dword v174, v216, s[14:15] offset:3584
	global_load_dword v175, v216, s[14:15] offset:3840
	s_add_u32 s14, s24, 0x2000
	s_addc_u32 s15, s25, 0
	global_load_dword v176, v216, s[14:15]
	global_load_dword v177, v216, s[14:15] offset:256
	global_load_dword v178, v216, s[14:15] offset:512
	global_load_dword v179, v216, s[14:15] offset:768
	global_load_dword v180, v216, s[14:15] offset:1024
	global_load_dword v181, v216, s[14:15] offset:1280
	global_load_dword v182, v216, s[14:15] offset:1536
	global_load_dword v183, v216, s[14:15] offset:1792
	global_load_dword v184, v216, s[14:15] offset:2048
	global_load_dword v185, v216, s[14:15] offset:2304
	global_load_dword v186, v216, s[14:15] offset:2560
	global_load_dword v187, v216, s[14:15] offset:2816
	global_load_dword v188, v216, s[14:15] offset:3072
	global_load_dword v189, v216, s[14:15] offset:3328
	global_load_dword v190, v216, s[14:15] offset:3584
	global_load_dword v191, v216, s[14:15] offset:3840
	s_add_u32 s14, s24, 0x3000
	s_addc_u32 s15, s25, 0
	global_load_dword v192, v216, s[14:15]
	global_load_dword v193, v216, s[14:15] offset:256
	global_load_dword v194, v216, s[14:15] offset:512
	global_load_dword v195, v216, s[14:15] offset:768
	global_load_dword v196, v216, s[14:15] offset:1024
	global_load_dword v197, v216, s[14:15] offset:1280
	global_load_dword v198, v216, s[14:15] offset:1536
	global_load_dword v199, v216, s[14:15] offset:1792
	global_load_dword v200, v216, s[14:15] offset:2048
	global_load_dword v201, v216, s[14:15] offset:2304
	global_load_dword v202, v216, s[14:15] offset:2560
	global_load_dword v203, v216, s[14:15] offset:2816
	global_load_dword v204, v216, s[14:15] offset:3072
	global_load_dword v205, v216, s[14:15] offset:3328
	global_load_dword v206, v216, s[14:15] offset:3584
	global_load_dword v207, v216, s[14:15] offset:3840
	global_load_dword v208, v216, s[22:23]
	global_load_dword v209, v216, s[26:27]
	global_load_dword v210, v216, s[26:27] offset:256
	global_load_dword v211, v216, s[28:29]
	global_load_dword v212, v216, s[28:29] offset:256
	global_load_dword v213, v216, s[28:29] offset:512
	s_add_u32 s14, s84, 0x100000
	s_addc_u32 s15, s85, 0
	s_mov_b32 s3, s2
	s_waitcnt vmcnt(0)
.Lmlp_loop:
	s_lshl_b32 s8, s3, 3
	s_add_u32 s8, s8, s9
	v_cvt_f32_i32_e32 v218, s8
	v_mul_f32_e32 v219, 0x38800000, v218
	v_mul_f32_e32 v220, v214, v219
	v_floor_f32_e32 v220, v220
	v_fma_f32 v219, v214, v219, -v220
	v_cos_f32_e32 v221, v219
	v_sin_f32_e64 v222, -v219
	s_nop 0
	v_cndmask_b32_e64 v223, v222, v221, s[6:7]
	v_mul_f32_e32 v220, 0x38800200, v218
	v_cndmask_b32_e64 v223, v220, v223, s[4:5]
	v_mov_b32_e32 v224, v208
	s_nop 1
	v_readlane_b32 s16, v223, 0
	v_readlane_b32 s17, v223, 1
	v_readlane_b32 s18, v223, 2
	v_readlane_b32 s19, v223, 3
	v_readlane_b32 s20, v223, 4
	v_readlane_b32 s21, v223, 5
	v_readlane_b32 s22, v223, 6
	v_readlane_b32 s23, v223, 7
	v_readlane_b32 s24, v223, 8
	v_readlane_b32 s25, v223, 9
	v_readlane_b32 s26, v223, 10
	v_readlane_b32 s27, v223, 11
	v_readlane_b32 s28, v223, 12
	v_readlane_b32 s29, v223, 13
	v_readlane_b32 s30, v223, 14
	v_readlane_b32 s31, v223, 15
	v_fmac_f32_e32 v224, s16, v40
	v_fmac_f32_e32 v224, s17, v41
	v_fmac_f32_e32 v224, s18, v42
	v_fmac_f32_e32 v224, s19, v43
	v_fmac_f32_e32 v224, s20, v44
	v_fmac_f32_e32 v224, s21, v45
	v_fmac_f32_e32 v224, s22, v46
	v_fmac_f32_e32 v224, s23, v47
	v_fmac_f32_e32 v224, s24, v48
	v_fmac_f32_e32 v224, s25, v49
	v_fmac_f32_e32 v224, s26, v50
	v_fmac_f32_e32 v224, s27, v51
	v_fmac_f32_e32 v224, s28, v52
	v_fmac_f32_e32 v224, s29, v53
	v_fmac_f32_e32 v224, s30, v54
	v_fmac_f32_e32 v224, s31, v55
	v_readlane_b32 s16, v223, 16
	v_readlane_b32 s17, v223, 17
	v_readlane_b32 s18, v223, 18
	v_readlane_b32 s19, v223, 19
	v_readlane_b32 s20, v223, 20
	v_readlane_b32 s21, v223, 21
; DI void phase_prep(const P& p, int bid, int nb) {
;     ...
;       for (int i = 0; i < 33; ++i) acc += zb[tl * 36 + i] * p.emb_w[i * 64 + j];
;       ha[tl * 64 + j] = __sinf(p.freq[j] * acc);
;       __syncthreads();
;       acc = p.mlp_b[j];
; #pragma unroll 8
;       for (int i = 0; i < 64; ++i) acc += ha[tl * 64 + i] * p.mlp_w[i * 64 + j];
	v_readlane_b32 s22, v223, 22
	v_readlane_b32 s23, v223, 23
	v_readlane_b32 s24, v223, 24
	v_readlane_b32 s25, v223, 25
	v_readlane_b32 s26, v223, 26
	v_readlane_b32 s27, v223, 27
	v_readlane_b32 s28, v223, 28
	v_readlane_b32 s29, v223, 29
	v_readlane_b32 s30, v223, 30
	v_readlane_b32 s31, v223, 31
	v_fmac_f32_e32 v224, s16, v56
	v_fmac_f32_e32 v224, s17, v57
	v_fmac_f32_e32 v224, s18, v58
	v_fmac_f32_e32 v224, s19, v59
	v_fmac_f32_e32 v224, s20, v60
	v_fmac_f32_e32 v224, s21, v61
	v_fmac_f32_e32 v224, s22, v62
	v_fmac_f32_e32 v224, s23, v63
	v_fmac_f32_e32 v224, s24, v64
	v_fmac_f32_e32 v224, s25, v65
	v_fmac_f32_e32 v224, s26, v66
	v_fmac_f32_e32 v224, s27, v67
	v_fmac_f32_e32 v224, s28, v68
	v_fmac_f32_e32 v224, s29, v69
	v_fmac_f32_e32 v224, s30, v70
	v_fmac_f32_e32 v224, s31, v71
	v_readlane_b32 s16, v223, 32
	s_nop 1
	v_fmac_f32_e32 v224, s16, v72
	v_mul_f32_e32 v224, v224, v211
	v_mul_f32_e32 v224, 0.15915494, v224
	v_sin_f32_e32 v225, v224
	v_mov_b32_e32 v224, v209
	s_nop 1
	v_readlane_b32 s16, v225, 0
	v_readlane_b32 s17, v225, 1
	v_readlane_b32 s18, v225, 2
	v_readlane_b32 s19, v225, 3
	v_readlane_b32 s20, v225, 4
	v_readlane_b32 s21, v225, 5
	v_readlane_b32 s22, v225, 6
	v_readlane_b32 s23, v225, 7
	v_readlane_b32 s24, v225, 8
	v_readlane_b32 s25, v225, 9
	v_readlane_b32 s26, v225, 10
	v_readlane_b32 s27, v225, 11
	v_readlane_b32 s28, v225, 12
	v_readlane_b32 s29, v225, 13
	v_readlane_b32 s30, v225, 14
	v_readlane_b32 s31, v225, 15
	v_fmac_f32_e32 v224, s16, v80
	v_fmac_f32_e32 v224, s17, v81
	v_fmac_f32_e32 v224, s18, v82
	v_fmac_f32_e32 v224, s19, v83
	v_fmac_f32_e32 v224, s20, v84
	v_fmac_f32_e32 v224, s21, v85
	v_fmac_f32_e32 v224, s22, v86
	v_fmac_f32_e32 v224, s23, v87
	v_fmac_f32_e32 v224, s24, v88
	v_fmac_f32_e32 v224, s25, v89
	v_fmac_f32_e32 v224, s26, v90
	v_fmac_f32_e32 v224, s27, v91
	v_fmac_f32_e32 v224, s28, v92
	v_fmac_f32_e32 v224, s29, v93
	v_fmac_f32_e32 v224, s30, v94
	v_fmac_f32_e32 v224, s31, v95
	v_readlane_b32 s16, v225, 16
	v_readlane_b32 s17, v225, 17
	v_readlane_b32 s18, v225, 18
	v_readlane_b32 s19, v225, 19
	v_readlane_b32 s20, v225, 20
	v_readlane_b32 s21, v225, 21
	v_readlane_b32 s22, v225, 22
	v_readlane_b32 s23, v225, 23
	v_readlane_b32 s24, v225, 24
	v_readlane_b32 s25, v225, 25
	v_readlane_b32 s26, v225, 26
	v_readlane_b32 s27, v225, 27
	v_readlane_b32 s28, v225, 28
	v_readlane_b32 s29, v225, 29
	v_readlane_b32 s30, v225, 30
	v_readlane_b32 s31, v225, 31
	v_fmac_f32_e32 v224, s16, v96
	v_fmac_f32_e32 v224, s17, v97
	v_fmac_f32_e32 v224, s18, v98
	v_fmac_f32_e32 v224, s19, v99
	v_fmac_f32_e32 v224, s20, v100
	v_fmac_f32_e32 v224, s21, v101
	v_fmac_f32_e32 v224, s22, v102
	v_fmac_f32_e32 v224, s23, v103
	v_fmac_f32_e32 v224, s24, v104
	v_fmac_f32_e32 v224, s25, v105
	v_fmac_f32_e32 v224, s26, v106
	v_fmac_f32_e32 v224, s27, v107
	v_fmac_f32_e32 v224, s28, v108
	v_fmac_f32_e32 v224, s29, v109
	v_fmac_f32_e32 v224, s30, v110
	v_fmac_f32_e32 v224, s31, v111
	v_readlane_b32 s16, v225, 32
	v_readlane_b32 s17, v225, 33
	v_readlane_b32 s18, v225, 34
	v_readlane_b32 s19, v225, 35
	v_readlane_b32 s20, v225, 36
	v_readlane_b32 s21, v225, 37
	v_readlane_b32 s22, v225, 38
	v_readlane_b32 s23, v225, 39
	v_readlane_b32 s24, v225, 40
	v_readlane_b32 s25, v225, 41
	v_readlane_b32 s26, v225, 42
	v_readlane_b32 s27, v225, 43
	v_readlane_b32 s28, v225, 44
	v_readlane_b32 s29, v225, 45
	v_readlane_b32 s30, v225, 46
	v_readlane_b32 s31, v225, 47
	v_fmac_f32_e32 v224, s16, v112
	v_fmac_f32_e32 v224, s17, v113
	v_fmac_f32_e32 v224, s18, v114
	v_fmac_f32_e32 v224, s19, v115
	v_fmac_f32_e32 v224, s20, v116
	v_fmac_f32_e32 v224, s21, v117
	v_fmac_f32_e32 v224, s22, v118
	v_fmac_f32_e32 v224, s23, v119
	v_fmac_f32_e32 v224, s24, v120
	v_fmac_f32_e32 v224, s25, v121
	v_fmac_f32_e32 v224, s26, v122
	v_fmac_f32_e32 v224, s27, v123
	v_fmac_f32_e32 v224, s28, v124
	v_fmac_f32_e32 v224, s29, v125
	v_fmac_f32_e32 v224, s30, v126
	v_fmac_f32_e32 v224, s31, v127
	v_readlane_b32 s16, v225, 48
	v_readlane_b32 s17, v225, 49
	v_readlane_b32 s18, v225, 50
	v_readlane_b32 s19, v225, 51
	v_readlane_b32 s20, v225, 52
	v_readlane_b32 s21, v225, 53
	v_readlane_b32 s22, v225, 54
	v_readlane_b32 s23, v225, 55
	v_readlane_b32 s24, v225, 56
	v_readlane_b32 s25, v225, 57
	v_readlane_b32 s26, v225, 58
	v_readlane_b32 s27, v225, 59
	v_readlane_b32 s28, v225, 60
	v_readlane_b32 s29, v225, 61
	v_readlane_b32 s30, v225, 62
	v_readlane_b32 s31, v225, 63
	v_fmac_f32_e32 v224, s16, v128
	v_fmac_f32_e32 v224, s17, v129
	v_fmac_f32_e32 v224, s18, v130
	v_fmac_f32_e32 v224, s19, v131
	v_fmac_f32_e32 v224, s20, v132
	v_fmac_f32_e32 v224, s21, v133
	v_fmac_f32_e32 v224, s22, v134
	v_fmac_f32_e32 v224, s23, v135
; DI void phase_prep(const P& p, int bid, int nb) {
;     ...
;       for (int i = 0; i < 64; ++i) acc += ha[tl * 64 + i] * p.mlp_w[i * 64 + j];
;       hb[tl * 64 + j] = __sinf(p.freq[64 + j] * acc);
;       __syncthreads();
;       acc = p.mlp_b[64 + j];
; #pragma unroll 8
;       for (int i = 0; i < 64; ++i) acc += hb[tl * 64 + i] * p.mlp_w[4096 + i * 64 + j];
;       HDN[(size_t)t * 64 + j] = f2bf(__sinf(p.freq[128 + j] * acc));
	v_fmac_f32_e32 v224, s24, v136
	v_fmac_f32_e32 v224, s25, v137
	v_fmac_f32_e32 v224, s26, v138
	v_fmac_f32_e32 v224, s27, v139
	v_fmac_f32_e32 v224, s28, v140
	v_fmac_f32_e32 v224, s29, v141
	v_fmac_f32_e32 v224, s30, v142
	v_fmac_f32_e32 v224, s31, v143
	v_mul_f32_e32 v224, v224, v212
	v_mul_f32_e32 v224, 0.15915494, v224
	v_sin_f32_e32 v223, v224
	v_mov_b32_e32 v224, v210
	s_nop 1
	v_readlane_b32 s16, v223, 0
	v_readlane_b32 s17, v223, 1
	v_readlane_b32 s18, v223, 2
	v_readlane_b32 s19, v223, 3
	v_readlane_b32 s20, v223, 4
	v_readlane_b32 s21, v223, 5
	v_readlane_b32 s22, v223, 6
	v_readlane_b32 s23, v223, 7
	v_readlane_b32 s24, v223, 8
	v_readlane_b32 s25, v223, 9
	v_readlane_b32 s26, v223, 10
	v_readlane_b32 s27, v223, 11
	v_readlane_b32 s28, v223, 12
	v_readlane_b32 s29, v223, 13
	v_readlane_b32 s30, v223, 14
	v_readlane_b32 s31, v223, 15
	v_fmac_f32_e32 v224, s16, v144
	v_fmac_f32_e32 v224, s17, v145
	v_fmac_f32_e32 v224, s18, v146
	v_fmac_f32_e32 v224, s19, v147
	v_fmac_f32_e32 v224, s20, v148
	v_fmac_f32_e32 v224, s21, v149
	v_fmac_f32_e32 v224, s22, v150
	v_fmac_f32_e32 v224, s23, v151
	v_fmac_f32_e32 v224, s24, v152
	v_fmac_f32_e32 v224, s25, v153
	v_fmac_f32_e32 v224, s26, v154
	v_fmac_f32_e32 v224, s27, v155
	v_fmac_f32_e32 v224, s28, v156
	v_fmac_f32_e32 v224, s29, v157
	v_fmac_f32_e32 v224, s30, v158
	v_fmac_f32_e32 v224, s31, v159
	v_readlane_b32 s16, v223, 16
	v_readlane_b32 s17, v223, 17
	v_readlane_b32 s18, v223, 18
	v_readlane_b32 s19, v223, 19
	v_readlane_b32 s20, v223, 20
	v_readlane_b32 s21, v223, 21
	v_readlane_b32 s22, v223, 22
	v_readlane_b32 s23, v223, 23
	v_readlane_b32 s24, v223, 24
	v_readlane_b32 s25, v223, 25
	v_readlane_b32 s26, v223, 26
	v_readlane_b32 s27, v223, 27
	v_readlane_b32 s28, v223, 28
	v_readlane_b32 s29, v223, 29
	v_readlane_b32 s30, v223, 30
	v_readlane_b32 s31, v223, 31
	v_fmac_f32_e32 v224, s16, v160
	v_fmac_f32_e32 v224, s17, v161
	v_fmac_f32_e32 v224, s18, v162
	v_fmac_f32_e32 v224, s19, v163
	v_fmac_f32_e32 v224, s20, v164
	v_fmac_f32_e32 v224, s21, v165
	v_fmac_f32_e32 v224, s22, v166
	v_fmac_f32_e32 v224, s23, v167
	v_fmac_f32_e32 v224, s24, v168
	v_fmac_f32_e32 v224, s25, v169
	v_fmac_f32_e32 v224, s26, v170
	v_fmac_f32_e32 v224, s27, v171
	v_fmac_f32_e32 v224, s28, v172
	v_fmac_f32_e32 v224, s29, v173
	v_fmac_f32_e32 v224, s30, v174
	v_fmac_f32_e32 v224, s31, v175
	v_readlane_b32 s16, v223, 32
	v_readlane_b32 s17, v223, 33
	v_readlane_b32 s18, v223, 34
	v_readlane_b32 s19, v223, 35
	v_readlane_b32 s20, v223, 36
	v_readlane_b32 s21, v223, 37
	v_readlane_b32 s22, v223, 38
	v_readlane_b32 s23, v223, 39
	v_readlane_b32 s24, v223, 40
	v_readlane_b32 s25, v223, 41
	v_readlane_b32 s26, v223, 42
	v_readlane_b32 s27, v223, 43
	v_readlane_b32 s28, v223, 44
	v_readlane_b32 s29, v223, 45
	v_readlane_b32 s30, v223, 46
	v_readlane_b32 s31, v223, 47
	v_fmac_f32_e32 v224, s16, v176
	v_fmac_f32_e32 v224, s17, v177
	v_fmac_f32_e32 v224, s18, v178
	v_fmac_f32_e32 v224, s19, v179
	v_fmac_f32_e32 v224, s20, v180
	v_fmac_f32_e32 v224, s21, v181
	v_fmac_f32_e32 v224, s22, v182
	v_fmac_f32_e32 v224, s23, v183
	v_fmac_f32_e32 v224, s24, v184
	v_fmac_f32_e32 v224, s25, v185
	v_fmac_f32_e32 v224, s26, v186
	v_fmac_f32_e32 v224, s27, v187
	v_fmac_f32_e32 v224, s28, v188
	v_fmac_f32_e32 v224, s29, v189
	v_fmac_f32_e32 v224, s30, v190
	v_fmac_f32_e32 v224, s31, v191
	v_readlane_b32 s16, v223, 48
	v_readlane_b32 s17, v223, 49
	v_readlane_b32 s18, v223, 50
	v_readlane_b32 s19, v223, 51
	v_readlane_b32 s20, v223, 52
	v_readlane_b32 s21, v223, 53
	v_readlane_b32 s22, v223, 54
	v_readlane_b32 s23, v223, 55
	v_readlane_b32 s24, v223, 56
	v_readlane_b32 s25, v223, 57
	v_readlane_b32 s26, v223, 58
	v_readlane_b32 s27, v223, 59
	v_readlane_b32 s28, v223, 60
	v_readlane_b32 s29, v223, 61
	v_readlane_b32 s30, v223, 62
	v_readlane_b32 s31, v223, 63
	v_fmac_f32_e32 v224, s16, v192
	v_fmac_f32_e32 v224, s17, v193
	v_fmac_f32_e32 v224, s18, v194
	v_fmac_f32_e32 v224, s19, v195
	v_fmac_f32_e32 v224, s20, v196
	v_fmac_f32_e32 v224, s21, v197
	v_fmac_f32_e32 v224, s22, v198
	v_fmac_f32_e32 v224, s23, v199
	v_fmac_f32_e32 v224, s24, v200
	v_fmac_f32_e32 v224, s25, v201
	v_fmac_f32_e32 v224, s26, v202
	v_fmac_f32_e32 v224, s27, v203
	v_fmac_f32_e32 v224, s28, v204
	v_fmac_f32_e32 v224, s29, v205
	v_fmac_f32_e32 v224, s30, v206
	v_fmac_f32_e32 v224, s31, v207
	v_mul_f32_e32 v224, v224, v213
	v_mul_f32_e32 v224, 0.15915494, v224
	v_sin_f32_e32 v225, v224
	s_nop 0
	v_cvt_pk_bf16_f32 v225, v225, v225
	s_lshl_b32 s8, s8, 7
	s_add_u32 s16, s14, s8
	s_addc_u32 s17, s15, 0
	global_store_short v217, v225, s[16:17]
	s_add_i32 s3, s3, s88
	s_cmpk_gt_i32 s3, 0x7ff
	s_cbranch_scc0 .Lmlp_loop

; DI float bflo(unsigned u) { return __uint_as_float(u << 16); }
; DI float bfhi(unsigned u) { return __uint_as_float(u & 0xffff0000u); }
; DI void phase_mergeprep(const P& p, int bid, int nb) {
;     ...
;     for (int it = bid; it < 4096; it += nb) {
;       const int tr = it >> 4, ct = it & 15; const int t0 = tr * 64, c0 = ct * 64;
;       { const int c = tid >> 3, t8 = (tid & 7) * 8; const float* s0 = ZC + (size_t)(c0 + c) * 16384 + t0 + t8; const float* s1 = s0 + (size_t)1024 * 16384;
;         const f32x4 a0 = *(const f32x4*)s0, a1 = *(const f32x4*)(s0 + 4), b0 = *(const f32x4*)s1, b1 = *(const f32x4*)(s1 + 4);
; #pragma unroll
;         for (int e = 0; e < 4; ++e) { tile[c * 65 + t8 + e] = (f32x2){a0[e], b0[e]}; tile[c * 65 + t8 + 4 + e] = (f32x2){a1[e], b1[e]}; } }
;       __syncthreads();
;       const int t = tid >> 3, cg8 = (tid & 7) * 8;
; #pragma unroll
;       for (int b = 0; b < 2; ++b) {
;         float x0[8];
; #pragma unroll
;         for (int e = 0; e < 8; ++e) x0[e] = p.short_b[c0 + cg8 + e];
; #pragma unroll
;         for (int tap = 0; tap < 3; ++tap) { const int tt = t + tap - 1; if (tt < 0 || tt > 63) continue;
;           u32x4 a = *(const u32x4*)(ZH + ((size_t)b * 16384 + t0 + tt) * 1024 + c0 + cg8);
;           const float* w0 = p.short_w + tap * 3072 + c0 + cg8;
; #pragma unroll
;           for (int e = 0; e < 4; ++e) { x0[2 * e] += bflo(a[e]) * w0[2 * e]; x0[2 * e + 1] += bfhi(a[e]) * w0[2 * e + 1]; } }
.LBB0_511:
	s_or_b64 exec, exec, s[4:5]
	s_cmpk_gt_i32 s2, 0xfff
	s_cbranch_scc1 .LBB0_526
	s_waitcnt lgkmcnt(0)
	v_and_b32_e32 v1, 0x3ff, v0
	v_lshrrev_b32_e32 v2, 3, v1
	v_and_b32_e32 v3, 7, v1
	v_mul_u32_u24_e32 v4, 0x41, v2
	v_lshl_add_u32 v4, v3, 3, v4
	v_lshlrev_b32_e32 v4, 3, v4
	v_mul_u32_u24_e32 v5, 0x208, v3
	v_add_u32_e32 v5, v5, v2
	v_lshlrev_b32_e32 v5, 3, v5
	v_lshlrev_b32_e32 v6, 16, v2
	v_lshl_add_u32 v6, v3, 5, v6
	v_lshlrev_b32_e32 v8, 4, v3
	v_add_u32_e32 v7, -1, v2
	v_max_i32_e32 v7, 0, v7
	v_add_u32_e32 v9, 1, v2
	v_min_i32_e32 v9, 63, v9
	v_lshl_add_u32 v7, v7, 11, v8
	v_lshl_add_u32 v9, v9, 11, v8
	v_lshl_add_u32 v10, v2, 12, v8
	v_lshl_add_u32 v8, v2, 11, v8
	v_lshlrev_b32_e32 v13, 5, v3
	v_cmp_lt_u32_e32 vcc, 0, v2
	s_nop 1
	v_cndmask_b32_e64 v11, 0, 1.0, vcc
	v_cmp_gt_u32_e32 vcc, 63, v2
	s_nop 1
	v_cndmask_b32_e64 v12, 0, 1.0, vcc
	v_readlane_b32 s36, v254, 0
	v_readlane_b32 s37, v254, 1
	v_readlane_b32 s38, v254, 2
	v_readlane_b32 s39, v254, 3
	s_mov_b32 s3, s2
	s_mov_b32 s5, -1
	s_mov_b32 s28, 0
	s_lshr_b32 s6, s3, 4
	s_and_b32 s7, s3, 15
	s_lshl_b32 s10, s7, 22
	s_lshl_b32 s11, s6, 8
	s_add_u32 s10, s10, s11
	s_add_u32 s12, s84, s10
	s_addc_u32 s13, s85, 0
	s_add_u32 s12, s12, 0x33d00000
	s_addc_u32 s13, s13, 0
	s_add_u32 s14, s12, 0x4000000
	s_addc_u32 s15, s13, 0
	s_lshl_b32 s10, s6, 17
	s_lshl_b32 s11, s7, 7
	s_add_u32 s10, s10, s11
	s_add_u32 s16, s84, s10
	s_addc_u32 s17, s85, 0
	s_add_u32 s16, s16, 0x1fd00000
	s_addc_u32 s17, s17, 0
	s_add_u32 s18, s16, 0x2000000
	s_addc_u32 s19, s17, 0
	global_load_dwordx4 v[48:51], v6, s[12:13]
	global_load_dwordx4 v[52:55], v6, s[12:13] offset:16
	global_load_dwordx4 v[56:59], v6, s[14:15]
	global_load_dwordx4 v[60:63], v6, s[14:15] offset:16
	global_load_dwordx4 v[80:83], v7, s[16:17]
	global_load_dwordx4 v[84:87], v8, s[16:17]
	global_load_dwordx4 v[88:91], v9, s[16:17]
	global_load_dwordx4 v[92:95], v7, s[18:19]
	global_load_dwordx4 v[96:99], v8, s[18:19]
	global_load_dwordx4 v[100:103], v9, s[18:19]
.Lmp_half_A:
	s_and_b32 s7, s3, 15
	s_cmp_eq_u32 s7, s5
	s_cbranch_scc1 .Lmp_cok_A
	s_mov_b32 s5, s7
	s_lshl_b32 s10, s7, 8
	s_add_u32 s24, s38, s10
	s_addc_u32 s25, s39, 0
	global_load_dwordx4 v[16:19], v13, s[24:25]
	global_load_dwordx4 v[20:23], v13, s[24:25] offset:16
	s_add_u32 s24, s36, s10
	s_addc_u32 s25, s37, 0
	global_load_dwordx4 v[24:27], v13, s[24:25]
	global_load_dwordx4 v[28:31], v13, s[24:25] offset:16
	s_add_u32 s24, s24, 0x3000
	s_addc_u32 s25, s25, 0
	global_load_dwordx4 v[32:35], v13, s[24:25]
	global_load_dwordx4 v[36:39], v13, s[24:25] offset:16
	s_add_u32 s24, s24, 0x3000
	s_addc_u32 s25, s25, 0
	global_load_dwordx4 v[40:43], v13, s[24:25]
	global_load_dwordx4 v[44:47], v13, s[24:25] offset:16
	s_waitcnt vmcnt(0)
	v_mul_f32_e32 v24, v24, v11
	v_mul_f32_e32 v40, v40, v12
	v_mul_f32_e32 v25, v25, v11
	v_mul_f32_e32 v41, v41, v12
	v_mul_f32_e32 v26, v26, v11
	v_mul_f32_e32 v42, v42, v12
	v_mul_f32_e32 v27, v27, v11
	v_mul_f32_e32 v43, v43, v12
	v_mul_f32_e32 v28, v28, v11
	v_mul_f32_e32 v44, v44, v12
	v_mul_f32_e32 v29, v29, v11
	v_mul_f32_e32 v45, v45, v12
	v_mul_f32_e32 v30, v30, v11
	v_mul_f32_e32 v46, v46, v12
	v_mul_f32_e32 v31, v31, v11
	v_mul_f32_e32 v47, v47, v12
; DI unsigned pk2(float lo, float hi) { f32x2 v = {lo, hi}; bfv2 r = __builtin_convertvector(v, bfv2); return __builtin_bit_cast(unsigned, r); }
; DI float bflo(unsigned u) { return __uint_as_float(u << 16); }
; DI float bfhi(unsigned u) { return __uint_as_float(u & 0xffff0000u); }
; DI void phase_mergeprep(const P& p, int bid, int nb) {
;     ...
;       { const int c = tid >> 3, t8 = (tid & 7) * 8; const float* s0 = ZC + (size_t)(c0 + c) * 16384 + t0 + t8; const float* s1 = s0 + (size_t)1024 * 16384;
;         const f32x4 a0 = *(const f32x4*)s0, a1 = *(const f32x4*)(s0 + 4), b0 = *(const f32x4*)s1, b1 = *(const f32x4*)(s1 + 4);
; #pragma unroll
;         for (int e = 0; e < 4; ++e) { tile[c * 65 + t8 + e] = (f32x2){a0[e], b0[e]}; tile[c * 65 + t8 + 4 + e] = (f32x2){a1[e], b1[e]}; } }
;       __syncthreads();
;       const int t = tid >> 3, cg8 = (tid & 7) * 8;
; #pragma unroll
;       for (int b = 0; b < 2; ++b) {
;         float x0[8];
; #pragma unroll
;         for (int e = 0; e < 8; ++e) x0[e] = p.short_b[c0 + cg8 + e];
; #pragma unroll
;         for (int tap = 0; tap < 3; ++tap) { const int tt = t + tap - 1; if (tt < 0 || tt > 63) continue;
;           u32x4 a = *(const u32x4*)(ZH + ((size_t)b * 16384 + t0 + tt) * 1024 + c0 + cg8);
;           const float* w0 = p.short_w + tap * 3072 + c0 + cg8;
; #pragma unroll
;           for (int e = 0; e < 4; ++e) { x0[2 * e] += bflo(a[e]) * w0[2 * e]; x0[2 * e + 1] += bfhi(a[e]) * w0[2 * e + 1]; } }
;         float y[8];
; #pragma unroll
;         for (int e = 0; e < 8; ++e) { f32x2 yy = tile[(cg8 + e) * 65 + t]; y[e] = (b ? yy.y : yy.x) * x0[e]; }
;         u32x4 w; w.x = pk2(y[0], y[1]); w.y = pk2(y[2], y[3]); w.z = pk2(y[4], y[5]); w.w = pk2(y[6], y[7]);
;         *(u32x4*)(AM + ((size_t)b * 16384 + t0 + t) * 2048 + 1024 + c0 + cg8) = w;
.Lmp_cok_A:
	s_lshr_b32 s6, s3, 4
	s_lshl_b32 s10, s6, 18
	s_lshl_b32 s11, s7, 7
	s_add_u32 s10, s10, s11
	s_add_u32 s20, s84, s10
	s_addc_u32 s21, s85, 0
	s_add_u32 s20, s20, 0x1000800
	s_addc_u32 s21, s21, 0
	s_add_u32 s22, s20, 0x4000000
	s_addc_u32 s23, s21, 0
	s_add_i32 s27, s3, s88
	s_cmpk_lt_i32 s27, 0x1000
	s_cselect_b32 s26, 1, 0
	s_cselect_b32 s0, s27, s3
	s_lshr_b32 s6, s0, 4
	s_and_b32 s7, s0, 15
	s_lshl_b32 s10, s7, 22
	s_lshl_b32 s11, s6, 8
	s_add_u32 s10, s10, s11
	s_add_u32 s12, s84, s10
	s_addc_u32 s13, s85, 0
	s_add_u32 s12, s12, 0x33d00000
	s_addc_u32 s13, s13, 0
	s_add_u32 s14, s12, 0x4000000
	s_addc_u32 s15, s13, 0
	s_lshl_b32 s10, s6, 17
	s_lshl_b32 s11, s7, 7
	s_add_u32 s10, s10, s11
	s_add_u32 s16, s84, s10
	s_addc_u32 s17, s85, 0
	s_add_u32 s16, s16, 0x1fd00000
	s_addc_u32 s17, s17, 0
	s_add_u32 s18, s16, 0x2000000
	s_addc_u32 s19, s17, 0
	global_load_dwordx4 v[64:67], v6, s[12:13]
	global_load_dwordx4 v[68:71], v6, s[12:13] offset:16
	global_load_dwordx4 v[72:75], v6, s[14:15]
	global_load_dwordx4 v[76:79], v6, s[14:15] offset:16
	global_load_dwordx4 v[104:107], v7, s[16:17]
	global_load_dwordx4 v[108:111], v8, s[16:17]
	global_load_dwordx4 v[112:115], v9, s[16:17]
	global_load_dwordx4 v[116:119], v7, s[18:19]
	global_load_dwordx4 v[120:123], v8, s[18:19]
	global_load_dwordx4 v[124:127], v9, s[18:19]
	v_add_u32_e32 v14, s28, v4
	v_add_u32_e32 v15, s28, v5
	s_xor_b32 s28, s28, 0x8200
	s_waitcnt vmcnt(16)
	ds_write2_b32 v14, v48, v56 offset0:0 offset1:1
	ds_write2_b32 v14, v49, v57 offset0:2 offset1:3
	ds_write2_b32 v14, v50, v58 offset0:4 offset1:5
	ds_write2_b32 v14, v51, v59 offset0:6 offset1:7
	ds_write2_b32 v14, v52, v60 offset0:8 offset1:9
	ds_write2_b32 v14, v53, v61 offset0:10 offset1:11
	ds_write2_b32 v14, v54, v62 offset0:12 offset1:13
	ds_write2_b32 v14, v55, v63 offset0:14 offset1:15
	s_waitcnt lgkmcnt(0)
	s_barrier
	ds_read_b64 v[128:129], v15
	ds_read_b64 v[130:131], v15 offset:520
	ds_read_b64 v[132:133], v15 offset:1040
	ds_read_b64 v[134:135], v15 offset:1560
	ds_read_b64 v[136:137], v15 offset:2080
	ds_read_b64 v[138:139], v15 offset:2600
	ds_read_b64 v[140:141], v15 offset:3120
	ds_read_b64 v[142:143], v15 offset:3640
	s_waitcnt vmcnt(10)
	v_lshlrev_b32_e32 v152, 16, v80
	v_and_b32_e32 v153, 0xffff0000, v80
	v_lshlrev_b32_e32 v154, 16, v81
	v_and_b32_e32 v155, 0xffff0000, v81
	v_lshlrev_b32_e32 v156, 16, v82
	v_and_b32_e32 v157, 0xffff0000, v82
	v_lshlrev_b32_e32 v158, 16, v83
	v_and_b32_e32 v159, 0xffff0000, v83
	v_fma_f32 v144, v152, v24, v16
	v_fma_f32 v145, v153, v25, v17
	v_fma_f32 v146, v154, v26, v18
	v_fma_f32 v147, v155, v27, v19
	v_fma_f32 v148, v156, v28, v20
	v_fma_f32 v149, v157, v29, v21
	v_fma_f32 v150, v158, v30, v22
	v_fma_f32 v151, v159, v31, v23
	v_lshlrev_b32_e32 v152, 16, v84
	v_and_b32_e32 v153, 0xffff0000, v84
	v_lshlrev_b32_e32 v154, 16, v85
	v_and_b32_e32 v155, 0xffff0000, v85
	v_lshlrev_b32_e32 v156, 16, v86
	v_and_b32_e32 v157, 0xffff0000, v86
	v_lshlrev_b32_e32 v158, 16, v87
	v_and_b32_e32 v159, 0xffff0000, v87
	v_fmac_f32_e32 v144, v152, v32
	v_fmac_f32_e32 v145, v153, v33
	v_fmac_f32_e32 v146, v154, v34
	v_fmac_f32_e32 v147, v155, v35
	v_fmac_f32_e32 v148, v156, v36
	v_fmac_f32_e32 v149, v157, v37
	v_fmac_f32_e32 v150, v158, v38
	v_fmac_f32_e32 v151, v159, v39
	v_lshlrev_b32_e32 v152, 16, v88
	v_and_b32_e32 v153, 0xffff0000, v88
	v_lshlrev_b32_e32 v154, 16, v89
	v_and_b32_e32 v155, 0xffff0000, v89
	v_lshlrev_b32_e32 v156, 16, v90
	v_and_b32_e32 v157, 0xffff0000, v90
	v_lshlrev_b32_e32 v158, 16, v91
	v_and_b32_e32 v159, 0xffff0000, v91
	v_fmac_f32_e32 v144, v152, v40
	v_fmac_f32_e32 v145, v153, v41
	v_fmac_f32_e32 v146, v154, v42
	v_fmac_f32_e32 v147, v155, v43
	v_fmac_f32_e32 v148, v156, v44
	v_fmac_f32_e32 v149, v157, v45
	v_fmac_f32_e32 v150, v158, v46
	v_fmac_f32_e32 v151, v159, v47
	s_waitcnt lgkmcnt(0)
	v_mul_f32_e32 v144, v128, v144
	v_mul_f32_e32 v145, v130, v145
	v_mul_f32_e32 v146, v132, v146
	v_mul_f32_e32 v147, v134, v147
	v_mul_f32_e32 v148, v136, v148
	v_mul_f32_e32 v149, v138, v149
	v_mul_f32_e32 v150, v140, v150
	v_mul_f32_e32 v151, v142, v151
	v_cvt_pk_bf16_f32 v160, v144, v145
	v_cvt_pk_bf16_f32 v161, v146, v147
	v_cvt_pk_bf16_f32 v162, v148, v149
	v_cvt_pk_bf16_f32 v163, v150, v151
	global_store_dwordx4 v10, v[160:163], s[20:21]
	v_lshlrev_b32_e32 v152, 16, v92
	v_and_b32_e32 v153, 0xffff0000, v92
	v_lshlrev_b32_e32 v154, 16, v93
	v_and_b32_e32 v155, 0xffff0000, v93
	v_lshlrev_b32_e32 v156, 16, v94
	v_and_b32_e32 v157, 0xffff0000, v94
	v_lshlrev_b32_e32 v158, 16, v95
	v_and_b32_e32 v159, 0xffff0000, v95
	v_fma_f32 v144, v152, v24, v16
	v_fma_f32 v145, v153, v25, v17
	v_fma_f32 v146, v154, v26, v18
	v_fma_f32 v147, v155, v27, v19
	v_fma_f32 v148, v156, v28, v20
	v_fma_f32 v149, v157, v29, v21
	v_fma_f32 v150, v158, v30, v22
	v_fma_f32 v151, v159, v31, v23
	v_lshlrev_b32_e32 v152, 16, v96
	v_and_b32_e32 v153, 0xffff0000, v96
	v_lshlrev_b32_e32 v154, 16, v97
	v_and_b32_e32 v155, 0xffff0000, v97
	v_lshlrev_b32_e32 v156, 16, v98
	v_and_b32_e32 v157, 0xffff0000, v98
	v_lshlrev_b32_e32 v158, 16, v99
	v_and_b32_e32 v159, 0xffff0000, v99
	v_fmac_f32_e32 v144, v152, v32
	v_fmac_f32_e32 v145, v153, v33
	v_fmac_f32_e32 v146, v154, v34
	v_fmac_f32_e32 v147, v155, v35
	v_fmac_f32_e32 v148, v156, v36
	v_fmac_f32_e32 v149, v157, v37
	v_fmac_f32_e32 v150, v158, v38
	v_fmac_f32_e32 v151, v159, v39
	v_lshlrev_b32_e32 v152, 16, v100
	v_and_b32_e32 v153, 0xffff0000, v100
	v_lshlrev_b32_e32 v154, 16, v101
	v_and_b32_e32 v155, 0xffff0000, v101
	v_lshlrev_b32_e32 v156, 16, v102
	v_and_b32_e32 v157, 0xffff0000, v102
	v_lshlrev_b32_e32 v158, 16, v103
	v_and_b32_e32 v159, 0xffff0000, v103
	v_fmac_f32_e32 v144, v152, v40
	v_fmac_f32_e32 v145, v153, v41
	v_fmac_f32_e32 v146, v154, v42
	v_fmac_f32_e32 v147, v155, v43
	v_fmac_f32_e32 v148, v156, v44
	v_fmac_f32_e32 v149, v157, v45
	v_fmac_f32_e32 v150, v158, v46
	v_fmac_f32_e32 v151, v159, v47
	v_mul_f32_e32 v144, v129, v144
	v_mul_f32_e32 v145, v131, v145
	v_mul_f32_e32 v146, v133, v146
	v_mul_f32_e32 v147, v135, v147
	v_mul_f32_e32 v148, v137, v148
	v_mul_f32_e32 v149, v139, v149
	v_mul_f32_e32 v150, v141, v150
	v_mul_f32_e32 v151, v143, v151
	v_cvt_pk_bf16_f32 v164, v144, v145
	v_cvt_pk_bf16_f32 v165, v146, v147
	v_cvt_pk_bf16_f32 v166, v148, v149
	v_cvt_pk_bf16_f32 v167, v150, v151
	global_store_dwordx4 v10, v[164:167], s[22:23]
	s_cmp_eq_u32 s26, 0
	s_cbranch_scc1 .LBB0_526
	s_mov_b32 s3, s27

; DI unsigned pk2(float lo, float hi) { f32x2 v = {lo, hi}; bfv2 r = __builtin_convertvector(v, bfv2); return __builtin_bit_cast(unsigned, r); }
; DI float bflo(unsigned u) { return __uint_as_float(u << 16); }
; DI float bfhi(unsigned u) { return __uint_as_float(u & 0xffff0000u); }
; DI void phase_mergeprep(const P& p, int bid, int nb) {
;     ...
;       { const int c = tid >> 3, t8 = (tid & 7) * 8; const float* s0 = ZC + (size_t)(c0 + c) * 16384 + t0 + t8; const float* s1 = s0 + (size_t)1024 * 16384;
;         const f32x4 a0 = *(const f32x4*)s0, a1 = *(const f32x4*)(s0 + 4), b0 = *(const f32x4*)s1, b1 = *(const f32x4*)(s1 + 4);
; #pragma unroll
;         for (int e = 0; e < 4; ++e) { tile[c * 65 + t8 + e] = (f32x2){a0[e], b0[e]}; tile[c * 65 + t8 + 4 + e] = (f32x2){a1[e], b1[e]}; } }
;       __syncthreads();
;       const int t = tid >> 3, cg8 = (tid & 7) * 8;
; #pragma unroll
;       for (int b = 0; b < 2; ++b) {
;         float x0[8];
; #pragma unroll
;         for (int e = 0; e < 8; ++e) x0[e] = p.short_b[c0 + cg8 + e];
; #pragma unroll
;         for (int tap = 0; tap < 3; ++tap) { const int tt = t + tap - 1; if (tt < 0 || tt > 63) continue;
;           u32x4 a = *(const u32x4*)(ZH + ((size_t)b * 16384 + t0 + tt) * 1024 + c0 + cg8);
;           const float* w0 = p.short_w + tap * 3072 + c0 + cg8;
; #pragma unroll
;           for (int e = 0; e < 4; ++e) { x0[2 * e] += bflo(a[e]) * w0[2 * e]; x0[2 * e + 1] += bfhi(a[e]) * w0[2 * e + 1]; } }
;         float y[8];
; #pragma unroll
;         for (int e = 0; e < 8; ++e) { f32x2 yy = tile[(cg8 + e) * 65 + t]; y[e] = (b ? yy.y : yy.x) * x0[e]; }
;         u32x4 w; w.x = pk2(y[0], y[1]); w.y = pk2(y[2], y[3]); w.z = pk2(y[4], y[5]); w.w = pk2(y[6], y[7]);
;         *(u32x4*)(AM + ((size_t)b * 16384 + t0 + t) * 2048 + 1024 + c0 + cg8) = w;
.Lmp_cok_B:
	s_lshr_b32 s6, s3, 4
	s_lshl_b32 s10, s6, 18
	s_lshl_b32 s11, s7, 7
	s_add_u32 s10, s10, s11
	s_add_u32 s20, s84, s10
	s_addc_u32 s21, s85, 0
	s_add_u32 s20, s20, 0x1000800
	s_addc_u32 s21, s21, 0
	s_add_u32 s22, s20, 0x4000000
	s_addc_u32 s23, s21, 0
	s_add_i32 s27, s3, s88
	s_cmpk_lt_i32 s27, 0x1000
	s_cselect_b32 s26, 1, 0
	s_cselect_b32 s0, s27, s3
	s_lshr_b32 s6, s0, 4
	s_and_b32 s7, s0, 15
	s_lshl_b32 s10, s7, 22
	s_lshl_b32 s11, s6, 8
	s_add_u32 s10, s10, s11
	s_add_u32 s12, s84, s10
	s_addc_u32 s13, s85, 0
	s_add_u32 s12, s12, 0x33d00000
	s_addc_u32 s13, s13, 0
	s_add_u32 s14, s12, 0x4000000
	s_addc_u32 s15, s13, 0
	s_lshl_b32 s10, s6, 17
	s_lshl_b32 s11, s7, 7
	s_add_u32 s10, s10, s11
	s_add_u32 s16, s84, s10
	s_addc_u32 s17, s85, 0
	s_add_u32 s16, s16, 0x1fd00000
	s_addc_u32 s17, s17, 0
	s_add_u32 s18, s16, 0x2000000
	s_addc_u32 s19, s17, 0
	global_load_dwordx4 v[48:51], v6, s[12:13]
	global_load_dwordx4 v[52:55], v6, s[12:13] offset:16
	global_load_dwordx4 v[56:59], v6, s[14:15]
	global_load_dwordx4 v[60:63], v6, s[14:15] offset:16
	global_load_dwordx4 v[80:83], v7, s[16:17]
	global_load_dwordx4 v[84:87], v8, s[16:17]
	global_load_dwordx4 v[88:91], v9, s[16:17]
	global_load_dwordx4 v[92:95], v7, s[18:19]
	global_load_dwordx4 v[96:99], v8, s[18:19]
	global_load_dwordx4 v[100:103], v9, s[18:19]
	v_add_u32_e32 v14, s28, v4
	v_add_u32_e32 v15, s28, v5
	s_xor_b32 s28, s28, 0x8200
	s_waitcnt vmcnt(16)
	ds_write2_b32 v14, v64, v72 offset0:0 offset1:1
	ds_write2_b32 v14, v65, v73 offset0:2 offset1:3
	ds_write2_b32 v14, v66, v74 offset0:4 offset1:5
	ds_write2_b32 v14, v67, v75 offset0:6 offset1:7
	ds_write2_b32 v14, v68, v76 offset0:8 offset1:9
	ds_write2_b32 v14, v69, v77 offset0:10 offset1:11
	ds_write2_b32 v14, v70, v78 offset0:12 offset1:13
	ds_write2_b32 v14, v71, v79 offset0:14 offset1:15
	s_waitcnt lgkmcnt(0)
	s_barrier
	ds_read_b64 v[128:129], v15
	ds_read_b64 v[130:131], v15 offset:520
	ds_read_b64 v[132:133], v15 offset:1040
	ds_read_b64 v[134:135], v15 offset:1560
	ds_read_b64 v[136:137], v15 offset:2080
	ds_read_b64 v[138:139], v15 offset:2600
	ds_read_b64 v[140:141], v15 offset:3120
	ds_read_b64 v[142:143], v15 offset:3640
	s_waitcnt vmcnt(10)
	v_lshlrev_b32_e32 v152, 16, v104
	v_and_b32_e32 v153, 0xffff0000, v104
	v_lshlrev_b32_e32 v154, 16, v105
	v_and_b32_e32 v155, 0xffff0000, v105
	v_lshlrev_b32_e32 v156, 16, v106
	v_and_b32_e32 v157, 0xffff0000, v106
	v_lshlrev_b32_e32 v158, 16, v107
	v_and_b32_e32 v159, 0xffff0000, v107
	v_fma_f32 v144, v152, v24, v16
	v_fma_f32 v145, v153, v25, v17
	v_fma_f32 v146, v154, v26, v18
	v_fma_f32 v147, v155, v27, v19
	v_fma_f32 v148, v156, v28, v20
	v_fma_f32 v149, v157, v29, v21
	v_fma_f32 v150, v158, v30, v22
	v_fma_f32 v151, v159, v31, v23
	v_lshlrev_b32_e32 v152, 16, v108
	v_and_b32_e32 v153, 0xffff0000, v108
	v_lshlrev_b32_e32 v154, 16, v109
	v_and_b32_e32 v155, 0xffff0000, v109
	v_lshlrev_b32_e32 v156, 16, v110
	v_and_b32_e32 v157, 0xffff0000, v110
	v_lshlrev_b32_e32 v158, 16, v111
	v_and_b32_e32 v159, 0xffff0000, v111
	v_fmac_f32_e32 v144, v152, v32
	v_fmac_f32_e32 v145, v153, v33
	v_fmac_f32_e32 v146, v154, v34
	v_fmac_f32_e32 v147, v155, v35
	v_fmac_f32_e32 v148, v156, v36
	v_fmac_f32_e32 v149, v157, v37
	v_fmac_f32_e32 v150, v158, v38
	v_fmac_f32_e32 v151, v159, v39
	v_lshlrev_b32_e32 v152, 16, v112
	v_and_b32_e32 v153, 0xffff0000, v112
	v_lshlrev_b32_e32 v154, 16, v113
	v_and_b32_e32 v155, 0xffff0000, v113
	v_lshlrev_b32_e32 v156, 16, v114
	v_and_b32_e32 v157, 0xffff0000, v114
	v_lshlrev_b32_e32 v158, 16, v115
	v_and_b32_e32 v159, 0xffff0000, v115
	v_fmac_f32_e32 v144, v152, v40
	v_fmac_f32_e32 v145, v153, v41
	v_fmac_f32_e32 v146, v154, v42
	v_fmac_f32_e32 v147, v155, v43
	v_fmac_f32_e32 v148, v156, v44
	v_fmac_f32_e32 v149, v157, v45
	v_fmac_f32_e32 v150, v158, v46
	v_fmac_f32_e32 v151, v159, v47
	s_waitcnt lgkmcnt(0)
	v_mul_f32_e32 v144, v128, v144
	v_mul_f32_e32 v145, v130, v145
	v_mul_f32_e32 v146, v132, v146
	v_mul_f32_e32 v147, v134, v147
	v_mul_f32_e32 v148, v136, v148
	v_mul_f32_e32 v149, v138, v149
	v_mul_f32_e32 v150, v140, v150
	v_mul_f32_e32 v151, v142, v151
	v_cvt_pk_bf16_f32 v160, v144, v145
	v_cvt_pk_bf16_f32 v161, v146, v147
	v_cvt_pk_bf16_f32 v162, v148, v149
	v_cvt_pk_bf16_f32 v163, v150, v151
	global_store_dwordx4 v10, v[160:163], s[20:21]
	v_lshlrev_b32_e32 v152, 16, v116
	v_and_b32_e32 v153, 0xffff0000, v116
	v_lshlrev_b32_e32 v154, 16, v117
	v_and_b32_e32 v155, 0xffff0000, v117
	v_lshlrev_b32_e32 v156, 16, v118
	v_and_b32_e32 v157, 0xffff0000, v118
	v_lshlrev_b32_e32 v158, 16, v119
	v_and_b32_e32 v159, 0xffff0000, v119
	v_fma_f32 v144, v152, v24, v16
	v_fma_f32 v145, v153, v25, v17
	v_fma_f32 v146, v154, v26, v18
	v_fma_f32 v147, v155, v27, v19
	v_fma_f32 v148, v156, v28, v20
	v_fma_f32 v149, v157, v29, v21
	v_fma_f32 v150, v158, v30, v22
	v_fma_f32 v151, v159, v31, v23
	v_lshlrev_b32_e32 v152, 16, v120
	v_and_b32_e32 v153, 0xffff0000, v120
	v_lshlrev_b32_e32 v154, 16, v121
	v_and_b32_e32 v155, 0xffff0000, v121
	v_lshlrev_b32_e32 v156, 16, v122
	v_and_b32_e32 v157, 0xffff0000, v122
	v_lshlrev_b32_e32 v158, 16, v123
	v_and_b32_e32 v159, 0xffff0000, v123
	v_fmac_f32_e32 v144, v152, v32
	v_fmac_f32_e32 v145, v153, v33
	v_fmac_f32_e32 v146, v154, v34
	v_fmac_f32_e32 v147, v155, v35
	v_fmac_f32_e32 v148, v156, v36
	v_fmac_f32_e32 v149, v157, v37
	v_fmac_f32_e32 v150, v158, v38
	v_fmac_f32_e32 v151, v159, v39
	v_lshlrev_b32_e32 v152, 16, v124
	v_and_b32_e32 v153, 0xffff0000, v124
	v_lshlrev_b32_e32 v154, 16, v125
	v_and_b32_e32 v155, 0xffff0000, v125
	v_lshlrev_b32_e32 v156, 16, v126
	v_and_b32_e32 v157, 0xffff0000, v126
	v_lshlrev_b32_e32 v158, 16, v127
	v_and_b32_e32 v159, 0xffff0000, v127
	v_fmac_f32_e32 v144, v152, v40
	v_fmac_f32_e32 v145, v153, v41
	v_fmac_f32_e32 v146, v154, v42
	v_fmac_f32_e32 v147, v155, v43
	v_fmac_f32_e32 v148, v156, v44
	v_fmac_f32_e32 v149, v157, v45
	v_fmac_f32_e32 v150, v158, v46
	v_fmac_f32_e32 v151, v159, v47
	v_mul_f32_e32 v144, v129, v144
	v_mul_f32_e32 v145, v131, v145
	v_mul_f32_e32 v146, v133, v146
	v_mul_f32_e32 v147, v135, v147
	v_mul_f32_e32 v148, v137, v148
	v_mul_f32_e32 v149, v139, v149
	v_mul_f32_e32 v150, v141, v150
	v_mul_f32_e32 v151, v143, v151
	v_cvt_pk_bf16_f32 v164, v144, v145
	v_cvt_pk_bf16_f32 v165, v146, v147
	v_cvt_pk_bf16_f32 v166, v148, v149
	v_cvt_pk_bf16_f32 v167, v150, v151
	global_store_dwordx4 v10, v[164:167], s[22:23]
	s_cmp_eq_u32 s26, 0
	s_cbranch_scc1 .LBB0_526
	s_mov_b32 s3, s27
	s_branch .Lmp_half_A
